# baseline (speedup 1.0000x reference)
; DEVFI float bf2f(bfraw h) { return __uint_as_float(((unsigned)h) << 16); }
; DEVFI bfraw f2bf(float x) { unsigned u = __float_as_uint(x); u += 0x7fffu + ((u >> 16) & 1u); return (bfraw)(u >> 16); }
; __global__ void __launch_bounds__(512) mega(Params p) {
;     ...
;         for (int bi = bid; bi < 128 * 8; bi += nb) {
;           int tz = tid; asm volatile("" : "+v"(tz));
;           const int ew = __builtin_amdgcn_readfirstlane(tz >> 6), lz = tz & 63, fr = tz & 15, fq = (tz >> 4) & 3;
;           const int head = bi & 7, chunk = bi >> 3;
;           const float lgf = lgt_[head], lgb = lgt_[8 + head];
;           const bfraw* vt = rvt_ + ((long)(chunk * 8 + head) * 128) * 128;
;           const bfraw* kt = rkt_ + ((long)(chunk * 8 + head) * 128) * 128;
;           __syncthreads();
; #pragma unroll
;           for (int g = 0; g < 4; ++g) { const int blk = g * 8 + ew, row = blk * 4 + (lz >> 4), c = (lz ^ row) & 15;
;             __builtin_amdgcn_global_load_lds((const unsigned*)(vt + row * 128 + c * 8), (unsigned*)(shm + blk * 1024), 16, 0, 0); }
;           bf16x8 Af[4], Ab[4];
; #pragma unroll
;           for (int sx = 0; sx < 4; ++sx) { const bf16x8 raw = *(const bf16x8*)(kt + (ew * 16 + fr) * 128 + sx * 32 + fq * 8);
; #pragma unroll
;             for (int i = 0; i < 8; ++i) { const int mm = sx * 32 + fq * 8 + i; const float x = bf2f((bfraw)raw[i]);
;               Af[sx][i] = (short)f2bf(x * __expf(lgf * (float)(127 - mm))); Ab[sx][i] = (short)f2bf(x * __expf(lgb * (float)mm)); } }
.LBB0_2423:
	v_mov_b32_e32 v2, v8
	s_nop 0
	v_readfirstlane_b32 s17, v2
	s_ashr_i32 s18, s17, 6
	s_and_b32 s17, s15, 7
	s_lshl_b32 s17, s17, 2
	v_bfe_u32 v5, v2, 4, 2
	v_mov_b32_e32 v0, s17
	s_lshl_b32 s17, s18, 2
	global_load_dword v11, v0, s[6:7]
	global_load_dword v10, v0, s[6:7] offset:32
	v_or_b32_e32 v0, s17, v5
	v_bitop3_b32 v3, v0, 15, v2 bitop3:0x48
	v_lshlrev_b32_e32 v0, 7, v5
	v_lshl_or_b32 v0, s18, 9, v0
	v_ashrrev_i32_e32 v1, 31, v0
	v_lshlrev_b64 v[0:1], 1, v[0:1]
	s_add_u32 s20, s12, s70
	v_lshl_or_b32 v0, v3, 4, v0
	s_addc_u32 s21, s14, s71
	v_lshl_add_u64 v[0:1], s[20:21], 0, v[0:1]
	s_lshl_b32 m0, s18, 10
	s_add_i32 s19, s18, 8
	s_barrier
	global_load_lds_dwordx4 v[0:1], off
	v_lshl_or_b32 v0, s19, 2, v5
	s_add_i32 s22, s17, 32
	v_bitop3_b32 v3, v0, 15, v2 bitop3:0x48
	v_or_b32_e32 v0, s22, v5
	v_lshlrev_b32_e32 v0, 7, v0
	v_ashrrev_i32_e32 v1, 31, v0
	v_lshlrev_b64 v[0:1], 1, v[0:1]
	v_lshl_or_b32 v0, v3, 4, v0
	v_lshl_add_u64 v[0:1], s[20:21], 0, v[0:1]
	s_lshl_b32 m0, s19, 10
	s_add_i32 s19, s18, 16
	global_load_lds_dwordx4 v[0:1], off
	v_lshl_or_b32 v0, s19, 2, v5
	s_add_i32 s22, s17, 64
	v_bitop3_b32 v3, v0, 15, v2 bitop3:0x48
	v_or_b32_e32 v0, s22, v5
	v_lshlrev_b32_e32 v0, 7, v0
	v_ashrrev_i32_e32 v1, 31, v0
	v_lshlrev_b64 v[0:1], 1, v[0:1]
	v_lshl_or_b32 v0, v3, 4, v0
	v_lshl_add_u64 v[0:1], s[20:21], 0, v[0:1]
	s_lshl_b32 m0, s19, 10
	s_add_i32 s19, s18, 24
	global_load_lds_dwordx4 v[0:1], off
	v_lshl_or_b32 v0, s19, 2, v5
	s_addk_i32 s17, 0x60
	v_bitop3_b32 v3, v0, 15, v2 bitop3:0x48
	v_or_b32_e32 v0, s17, v5
	v_lshlrev_b32_e32 v0, 7, v0
	v_ashrrev_i32_e32 v1, 31, v0
	v_lshlrev_b64 v[0:1], 1, v[0:1]
	v_lshl_or_b32 v0, v3, 4, v0
	v_lshl_add_u64 v[0:1], s[20:21], 0, v[0:1]
	s_lshl_b32 m0, s19, 10
	v_and_b32_e32 v12, 15, v2
	global_load_lds_dwordx4 v[0:1], off
	v_lshlrev_b32_e32 v0, 7, v12
	v_lshl_or_b32 v0, s18, 11, v0
	v_ashrrev_i32_e32 v1, 31, v0
	v_lshlrev_b64 v[0:1], 1, v[0:1]
	s_add_u32 s20, s8, s70
	v_lshl_or_b32 v0, v5, 4, v0
	s_addc_u32 s21, s9, s71
	v_lshl_add_u64 v[0:1], s[20:21], 0, v[0:1]
	s_mov_b32 s17, 0x15720000
	v_add_co_u32_e32 v6, vcc, s17, v0
	v_lshrrev_b32_e32 v9, 4, v2
	s_nop 0
	v_addc_co_u32_e32 v7, vcc, 0, v1, vcc
	global_load_dwordx4 v[0:3], v[6:7], off
	global_load_dwordx4 v[124:127], v[6:7], off offset:64
	global_load_dwordx4 v[160:163], v[6:7], off offset:128
	global_load_dwordx4 v[164:167], v[6:7], off offset:192
	v_lshlrev_b32_e32 v4, 3, v5
	v_xor_b32_e32 v13, 0x7f, v4
	v_cvt_f32_ubyte0_e32 v13, v13
	v_xor_b32_e32 v15, 0x7e, v4
	v_cvt_f32_ubyte0_e32 v15, v15
	v_lshlrev_b32_e32 v176, 8, v12
	s_waitcnt vmcnt(0)
	v_mul_f32_e32 v13, v11, v13
	v_mul_f32_e32 v13, 0x3fb8aa3b, v13
	v_exp_f32_e32 v14, v13
	v_cvt_f32_ubyte0_e32 v13, v4
	v_mul_f32_e32 v13, v10, v13
	v_mul_f32_e32 v13, 0x3fb8aa3b, v13
	v_exp_f32_e32 v16, v13
	v_or_b32_e32 v13, 1, v4
	v_cvt_f32_ubyte0_e32 v13, v13
	v_mul_f32_e32 v15, v11, v15
	v_mul_f32_e32 v13, v10, v13
	v_mul_f32_e32 v15, 0x3fb8aa3b, v15
	v_mul_f32_e32 v13, 0x3fb8aa3b, v13
	v_exp_f32_e32 v15, v15
	v_exp_f32_e32 v17, v13
	v_xor_b32_e32 v13, 0x7d, v4
	v_cvt_f32_ubyte0_e32 v13, v13
	v_mul_f32_e32 v13, v11, v13
	v_mul_f32_e32 v13, 0x3fb8aa3b, v13
	v_and_b32_e32 v19, 0xffff0000, v0
	v_lshlrev_b32_e32 v18, 16, v0
	v_or_b32_e32 v0, 2, v4
	v_cvt_f32_ubyte0_e32 v0, v0
	v_mul_f32_e32 v0, v10, v0
	v_mul_f32_e32 v0, 0x3fb8aa3b, v0
	v_pk_mul_f32 v[24:25], v[16:17], v[18:19]
	v_pk_mul_f32 v[14:15], v[14:15], v[18:19]
	v_exp_f32_e32 v16, v13
	v_exp_f32_e32 v18, v0
	v_or_b32_e32 v0, 3, v4
	v_xor_b32_e32 v13, 0x7c, v4
	v_cvt_f32_ubyte0_e32 v13, v13
	v_cvt_f32_ubyte0_e32 v0, v0
	v_mul_f32_e32 v13, v11, v13
	v_mul_f32_e32 v0, v10, v0
	v_mul_f32_e32 v13, 0x3fb8aa3b, v13
	v_mul_f32_e32 v0, 0x3fb8aa3b, v0
	v_exp_f32_e32 v17, v13
	v_exp_f32_e32 v19, v0
	v_or_b32_e32 v13, 4, v4
	v_cvt_f32_ubyte0_e32 v13, v13
	v_mul_f32_e32 v13, v10, v13
	v_and_b32_e32 v21, 0xffff0000, v1
	v_lshlrev_b32_e32 v20, 16, v1
	v_mul_f32_e32 v13, 0x3fb8aa3b, v13
	v_pk_mul_f32 v[0:1], v[18:19], v[20:21]
	v_pk_mul_f32 v[16:17], v[16:17], v[20:21]
	v_xor_b32_e32 v18, 0x7b, v4
	v_exp_f32_e32 v20, v13
	v_or_b32_e32 v13, 5, v4
	v_xor_b32_e32 v19, 0x7a, v4
	v_cvt_f32_ubyte0_e32 v18, v18
	v_cvt_f32_ubyte0_e32 v19, v19
	v_cvt_f32_ubyte0_e32 v13, v13
	v_mul_f32_e32 v18, v11, v18
	v_mul_f32_e32 v19, v11, v19
	v_mul_f32_e32 v13, v10, v13
	v_mul_f32_e32 v18, 0x3fb8aa3b, v18
	v_mul_f32_e32 v19, 0x3fb8aa3b, v19
	v_mul_f32_e32 v13, 0x3fb8aa3b, v13
	v_exp_f32_e32 v18, v18
	v_exp_f32_e32 v19, v19
	v_exp_f32_e32 v21, v13
	v_and_b32_e32 v23, 0xffff0000, v2
	v_lshlrev_b32_e32 v22, 16, v2
	v_or_b32_e32 v2, 6, v4
	v_xor_b32_e32 v13, 0x79, v4
	v_cvt_f32_ubyte0_e32 v13, v13
	v_cvt_f32_ubyte0_e32 v2, v2
	v_mul_f32_e32 v13, v11, v13
	v_mul_f32_e32 v2, v10, v2
	v_mul_f32_e32 v13, 0x3fb8aa3b, v13
	v_mul_f32_e32 v2, 0x3fb8aa3b, v2
	v_pk_mul_f32 v[26:27], v[20:21], v[22:23]
	v_pk_mul_f32 v[18:19], v[18:19], v[22:23]
	v_exp_f32_e32 v20, v13
	v_exp_f32_e32 v22, v2
	v_or_b32_e32 v2, 7, v4
	v_xor_b32_e32 v13, 0x78, v4
	v_cvt_f32_ubyte0_e32 v13, v13
	v_cvt_f32_ubyte0_e32 v2, v2
	v_mul_f32_e32 v13, v11, v13
	v_mul_f32_e32 v2, v10, v2
	v_mul_f32_e32 v13, 0x3fb8aa3b, v13
	v_mul_f32_e32 v2, 0x3fb8aa3b, v2
	v_exp_f32_e32 v21, v13
	v_exp_f32_e32 v23, v2
	v_and_b32_e32 v29, 0xffff0000, v3
	v_lshlrev_b32_e32 v28, 16, v3
	v_pk_mul_f32 v[2:3], v[22:23], v[28:29]
	v_pk_mul_f32 v[22:23], v[20:21], v[28:29]
	v_cvt_pk_bf16_f32 v13, v14, v14
	v_cvt_pk_bf16_f32 v14, v15, v15
	v_cvt_pk_bf16_f32 v15, v16, v16
	v_cvt_pk_bf16_f32 v16, v17, v17
	v_cvt_pk_bf16_f32 v17, v18, v18
	v_cvt_pk_bf16_f32 v19, v19, v19
	v_cvt_pk_bf16_f32 v21, v22, v22
	v_cvt_pk_bf16_f32 v23, v23, v23
	v_cvt_pk_bf16_f32 v18, v24, v24
	v_cvt_pk_bf16_f32 v20, v25, v25
	v_cvt_pk_bf16_f32 v22, v0, v0
	v_cvt_pk_bf16_f32 v24, v1, v1
	v_cvt_pk_bf16_f32 v25, v26, v26
	v_cvt_pk_bf16_f32 v26, v27, v27
	v_cvt_pk_bf16_f32 v27, v2, v2
	v_cvt_pk_bf16_f32 v28, v3, v3
	v_or_b32_e32 v29, 32, v4
	v_cvt_f32_ubyte0_e32 v29, v29
	v_mul_f32_e32 v29, v10, v29
	v_mul_f32_e32 v29, 0x3fb8aa3b, v29
	v_xor_b32_e32 v30, 0x5f, v4
	v_exp_f32_e32 v32, v29
	v_or_b32_e32 v29, 33, v4
	v_xor_b32_e32 v31, 0x5e, v4
	v_cvt_f32_ubyte0_e32 v30, v30
	v_cvt_f32_ubyte0_e32 v31, v31
	v_cvt_f32_ubyte0_e32 v29, v29
	v_mul_f32_e32 v30, v11, v30
	v_mul_f32_e32 v31, v11, v31
	v_mul_f32_e32 v29, v10, v29
	v_mul_f32_e32 v30, 0x3fb8aa3b, v30
	v_mul_f32_e32 v31, 0x3fb8aa3b, v31
	v_mul_f32_e32 v29, 0x3fb8aa3b, v29
	v_exp_f32_e32 v30, v30
	v_exp_f32_e32 v31, v31
	v_exp_f32_e32 v33, v29
	v_xor_b32_e32 v29, 0x5d, v4
	v_cvt_f32_ubyte0_e32 v29, v29
	v_mul_f32_e32 v29, v11, v29
	v_mul_f32_e32 v29, 0x3fb8aa3b, v29
	s_waitcnt vmcnt(0)
; DEVFI float bf2f(bfraw h) { return __uint_as_float(((unsigned)h) << 16); }
; DEVFI bfraw f2bf(float x) { unsigned u = __float_as_uint(x); u += 0x7fffu + ((u >> 16) & 1u); return (bfraw)(u >> 16); }
; #define WAIT_V0() asm volatile("s_waitcnt vmcnt(0)" ::: "memory")
; __global__ void __launch_bounds__(512) mega(Params p) {
;     ...
;           bf16x8 Af[4], Ab[4];
; #pragma unroll
;           for (int sx = 0; sx < 4; ++sx) { const bf16x8 raw = *(const bf16x8*)(kt + (ew * 16 + fr) * 128 + sx * 32 + fq * 8);
; #pragma unroll
;             for (int i = 0; i < 8; ++i) { const int mm = sx * 32 + fq * 8 + i; const float x = bf2f((bfraw)raw[i]);
;               Af[sx][i] = (short)f2bf(x * __expf(lgf * (float)(127 - mm))); Ab[sx][i] = (short)f2bf(x * __expf(lgb * (float)mm)); } }
;           WAIT_V0(); __syncthreads();
	v_and_b32_e32 v35, 0xffff0000, v124
	v_lshlrev_b32_e32 v34, 16, v124
	v_or_b32_e32 v0, 34, v4
	v_cvt_f32_ubyte0_e32 v0, v0
	v_mul_f32_e32 v0, v10, v0
	v_mul_f32_e32 v0, 0x3fb8aa3b, v0
	v_pk_mul_f32 v[40:41], v[32:33], v[34:35]
	v_pk_mul_f32 v[30:31], v[30:31], v[34:35]
	v_exp_f32_e32 v32, v29
	v_exp_f32_e32 v34, v0
	v_or_b32_e32 v0, 35, v4
	v_xor_b32_e32 v29, 0x5c, v4
	v_cvt_f32_ubyte0_e32 v29, v29
	v_cvt_f32_ubyte0_e32 v0, v0
	v_mul_f32_e32 v29, v11, v29
	v_mul_f32_e32 v0, v10, v0
	v_mul_f32_e32 v29, 0x3fb8aa3b, v29
	v_mul_f32_e32 v0, 0x3fb8aa3b, v0
	v_exp_f32_e32 v33, v29
	v_exp_f32_e32 v35, v0
	v_or_b32_e32 v29, 36, v4
	v_cvt_f32_ubyte0_e32 v29, v29
	v_mul_f32_e32 v29, v10, v29
	v_and_b32_e32 v37, 0xffff0000, v125
	v_lshlrev_b32_e32 v36, 16, v125
	v_mul_f32_e32 v29, 0x3fb8aa3b, v29
	v_pk_mul_f32 v[0:1], v[34:35], v[36:37]
	v_pk_mul_f32 v[32:33], v[32:33], v[36:37]
	v_xor_b32_e32 v34, 0x5b, v4
	v_exp_f32_e32 v36, v29
	v_or_b32_e32 v29, 37, v4
	v_xor_b32_e32 v35, 0x5a, v4
	v_cvt_f32_ubyte0_e32 v34, v34
	v_cvt_f32_ubyte0_e32 v35, v35
	v_cvt_f32_ubyte0_e32 v29, v29
	v_mul_f32_e32 v34, v11, v34
	v_mul_f32_e32 v35, v11, v35
	v_mul_f32_e32 v29, v10, v29
	v_mul_f32_e32 v34, 0x3fb8aa3b, v34
	v_mul_f32_e32 v35, 0x3fb8aa3b, v35
	v_mul_f32_e32 v29, 0x3fb8aa3b, v29
	v_exp_f32_e32 v34, v34
	v_exp_f32_e32 v35, v35
	v_exp_f32_e32 v37, v29
	v_and_b32_e32 v39, 0xffff0000, v126
	v_lshlrev_b32_e32 v38, 16, v126
	v_or_b32_e32 v2, 38, v4
	v_xor_b32_e32 v29, 0x59, v4
	v_cvt_f32_ubyte0_e32 v29, v29
	v_cvt_f32_ubyte0_e32 v2, v2
	v_mul_f32_e32 v29, v11, v29
	v_mul_f32_e32 v2, v10, v2
	v_mul_f32_e32 v29, 0x3fb8aa3b, v29
	v_mul_f32_e32 v2, 0x3fb8aa3b, v2
	v_pk_mul_f32 v[42:43], v[36:37], v[38:39]
	v_pk_mul_f32 v[34:35], v[34:35], v[38:39]
	v_exp_f32_e32 v36, v29
	v_exp_f32_e32 v38, v2
	v_or_b32_e32 v2, 39, v4
	v_xor_b32_e32 v29, 0x58, v4
	v_cvt_f32_ubyte0_e32 v29, v29
	v_cvt_f32_ubyte0_e32 v2, v2
	v_mul_f32_e32 v29, v11, v29
	v_mul_f32_e32 v2, v10, v2
	v_mul_f32_e32 v29, 0x3fb8aa3b, v29
	v_mul_f32_e32 v2, 0x3fb8aa3b, v2
	v_exp_f32_e32 v37, v29
	v_exp_f32_e32 v39, v2
	v_and_b32_e32 v45, 0xffff0000, v127
	v_lshlrev_b32_e32 v44, 16, v127
	v_pk_mul_f32 v[2:3], v[38:39], v[44:45]
	v_pk_mul_f32 v[38:39], v[36:37], v[44:45]
	v_cvt_pk_bf16_f32 v29, v30, v30
	v_cvt_pk_bf16_f32 v30, v31, v31
	v_cvt_pk_bf16_f32 v31, v32, v32
	v_cvt_pk_bf16_f32 v32, v33, v33
	v_cvt_pk_bf16_f32 v33, v34, v34
	v_cvt_pk_bf16_f32 v34, v35, v35
	v_cvt_pk_bf16_f32 v37, v38, v38
	v_cvt_pk_bf16_f32 v38, v39, v39
	v_cvt_pk_bf16_f32 v35, v40, v40
	v_cvt_pk_bf16_f32 v36, v41, v41
	v_cvt_pk_bf16_f32 v39, v0, v0
	v_cvt_pk_bf16_f32 v40, v1, v1
	v_cvt_pk_bf16_f32 v41, v42, v42
	v_cvt_pk_bf16_f32 v42, v43, v43
	v_cvt_pk_bf16_f32 v43, v2, v2
	v_cvt_pk_bf16_f32 v44, v3, v3
	v_or_b32_e32 v45, 64, v4
	v_cvt_f32_ubyte0_e32 v45, v45
	v_mul_f32_e32 v45, v10, v45
	v_mul_f32_e32 v45, 0x3fb8aa3b, v45
	v_xor_b32_e32 v46, 63, v4
	v_exp_f32_e32 v48, v45
	v_or_b32_e32 v45, 0x41, v4
	v_xor_b32_e32 v47, 62, v4
	v_cvt_f32_ubyte0_e32 v46, v46
	v_cvt_f32_ubyte0_e32 v47, v47
	v_cvt_f32_ubyte0_e32 v45, v45
	v_mul_f32_e32 v46, v11, v46
	v_mul_f32_e32 v47, v11, v47
	v_mul_f32_e32 v45, v10, v45
	v_mul_f32_e32 v46, 0x3fb8aa3b, v46
	v_mul_f32_e32 v47, 0x3fb8aa3b, v47
	v_mul_f32_e32 v45, 0x3fb8aa3b, v45
	v_exp_f32_e32 v46, v46
	v_exp_f32_e32 v47, v47
	v_exp_f32_e32 v49, v45
	v_xor_b32_e32 v45, 61, v4
	v_cvt_f32_ubyte0_e32 v45, v45
	v_mul_f32_e32 v45, v11, v45
	v_mul_f32_e32 v45, 0x3fb8aa3b, v45
	s_waitcnt vmcnt(0)
	v_and_b32_e32 v51, 0xffff0000, v160
	v_lshlrev_b32_e32 v50, 16, v160
	v_or_b32_e32 v0, 0x42, v4
	v_cvt_f32_ubyte0_e32 v0, v0
	v_mul_f32_e32 v0, v10, v0
	v_mul_f32_e32 v0, 0x3fb8aa3b, v0
	v_pk_mul_f32 v[56:57], v[48:49], v[50:51]
	v_pk_mul_f32 v[46:47], v[46:47], v[50:51]
	v_exp_f32_e32 v48, v45
	v_exp_f32_e32 v50, v0
	v_or_b32_e32 v0, 0x43, v4
	v_xor_b32_e32 v45, 60, v4
	v_cvt_f32_ubyte0_e32 v45, v45
	v_cvt_f32_ubyte0_e32 v0, v0
	v_mul_f32_e32 v45, v11, v45
	v_mul_f32_e32 v0, v10, v0
	v_mul_f32_e32 v45, 0x3fb8aa3b, v45
	v_mul_f32_e32 v0, 0x3fb8aa3b, v0
	v_exp_f32_e32 v49, v45
	v_exp_f32_e32 v51, v0
	v_or_b32_e32 v45, 0x44, v4
	v_cvt_f32_ubyte0_e32 v45, v45
	v_mul_f32_e32 v45, v10, v45
	v_and_b32_e32 v53, 0xffff0000, v161
	v_lshlrev_b32_e32 v52, 16, v161
	v_mul_f32_e32 v45, 0x3fb8aa3b, v45
	v_pk_mul_f32 v[0:1], v[50:51], v[52:53]
	v_pk_mul_f32 v[48:49], v[48:49], v[52:53]
	v_xor_b32_e32 v50, 59, v4
	v_exp_f32_e32 v52, v45
	v_or_b32_e32 v45, 0x45, v4
	v_xor_b32_e32 v51, 58, v4
	v_cvt_f32_ubyte0_e32 v50, v50
	v_cvt_f32_ubyte0_e32 v51, v51
	v_cvt_f32_ubyte0_e32 v45, v45
	v_mul_f32_e32 v50, v11, v50
	v_mul_f32_e32 v51, v11, v51
	v_mul_f32_e32 v45, v10, v45
	v_mul_f32_e32 v50, 0x3fb8aa3b, v50
	v_mul_f32_e32 v51, 0x3fb8aa3b, v51
	v_mul_f32_e32 v45, 0x3fb8aa3b, v45
	v_exp_f32_e32 v50, v50
	v_exp_f32_e32 v51, v51
	v_exp_f32_e32 v53, v45
	v_and_b32_e32 v55, 0xffff0000, v162
	v_lshlrev_b32_e32 v54, 16, v162
	v_or_b32_e32 v2, 0x46, v4
	v_xor_b32_e32 v45, 57, v4
	v_cvt_f32_ubyte0_e32 v45, v45
	v_cvt_f32_ubyte0_e32 v2, v2
	v_mul_f32_e32 v45, v11, v45
	v_mul_f32_e32 v2, v10, v2
	v_mul_f32_e32 v45, 0x3fb8aa3b, v45
	v_mul_f32_e32 v2, 0x3fb8aa3b, v2
	v_pk_mul_f32 v[58:59], v[52:53], v[54:55]
	v_pk_mul_f32 v[50:51], v[50:51], v[54:55]
	v_exp_f32_e32 v52, v45
	v_exp_f32_e32 v54, v2
	v_or_b32_e32 v2, 0x47, v4
	v_xor_b32_e32 v45, 56, v4
	v_cvt_f32_ubyte0_e32 v45, v45
	v_cvt_f32_ubyte0_e32 v2, v2
	v_mul_f32_e32 v45, v11, v45
	v_mul_f32_e32 v2, v10, v2
	v_mul_f32_e32 v45, 0x3fb8aa3b, v45
	v_mul_f32_e32 v2, 0x3fb8aa3b, v2
	v_exp_f32_e32 v53, v45
	v_exp_f32_e32 v55, v2
	v_and_b32_e32 v61, 0xffff0000, v163
	v_lshlrev_b32_e32 v60, 16, v163
	v_pk_mul_f32 v[2:3], v[54:55], v[60:61]
	v_pk_mul_f32 v[54:55], v[52:53], v[60:61]
	v_cvt_pk_bf16_f32 v45, v46, v46
	v_cvt_pk_bf16_f32 v46, v47, v47
	v_cvt_pk_bf16_f32 v47, v48, v48
	v_cvt_pk_bf16_f32 v48, v49, v49
	v_cvt_pk_bf16_f32 v49, v50, v50
	v_cvt_pk_bf16_f32 v50, v51, v51
	v_cvt_pk_bf16_f32 v53, v54, v54
	v_cvt_pk_bf16_f32 v54, v55, v55
	v_cvt_pk_bf16_f32 v51, v56, v56
	v_cvt_pk_bf16_f32 v52, v57, v57
	v_cvt_pk_bf16_f32 v55, v0, v0
	v_cvt_pk_bf16_f32 v56, v1, v1
	v_cvt_pk_bf16_f32 v57, v58, v58
	v_cvt_pk_bf16_f32 v58, v59, v59
	v_cvt_pk_bf16_f32 v59, v2, v2
	v_cvt_pk_bf16_f32 v60, v3, v3
	v_or_b32_e32 v7, 0x60, v4
	v_cvt_f32_ubyte0_e32 v7, v7
	v_mul_f32_e32 v7, v10, v7
	v_mul_f32_e32 v7, 0x3fb8aa3b, v7
	v_xor_b32_e32 v6, 31, v4
	v_exp_f32_e32 v62, v7
	v_or_b32_e32 v61, 0x61, v4
	v_xor_b32_e32 v7, 30, v4
	v_cvt_f32_ubyte0_e32 v6, v6
	v_cvt_f32_ubyte0_e32 v7, v7
	v_cvt_f32_ubyte0_e32 v61, v61
	v_mul_f32_e32 v6, v11, v6
	v_mul_f32_e32 v7, v11, v7
	v_mul_f32_e32 v61, v10, v61
	v_mul_f32_e32 v6, 0x3fb8aa3b, v6
	v_mul_f32_e32 v7, 0x3fb8aa3b, v7
	v_mul_f32_e32 v61, 0x3fb8aa3b, v61
	v_exp_f32_e32 v6, v6
	v_exp_f32_e32 v7, v7
	v_exp_f32_e32 v63, v61
	v_xor_b32_e32 v61, 29, v4
	v_cvt_f32_ubyte0_e32 v61, v61
	v_mul_f32_e32 v61, v11, v61
	v_mul_f32_e32 v61, 0x3fb8aa3b, v61
	s_waitcnt vmcnt(0)
	s_waitcnt lgkmcnt(0)
	s_barrier
; DEVFI float bf2f(bfraw h) { return __uint_as_float(((unsigned)h) << 16); }
; DEVFI bfraw f2bf(float x) { unsigned u = __float_as_uint(x); u += 0x7fffu + ((u >> 16) & 1u); return (bfraw)(u >> 16); }
; #define SBAR() __builtin_amdgcn_sched_barrier(0)
; #define WAIT_V0() asm volatile("s_waitcnt vmcnt(0)" ::: "memory")
; __global__ void __launch_bounds__(512) mega(Params p) {
;     ...
;           for (int sx = 0; sx < 4; ++sx) { const bf16x8 raw = *(const bf16x8*)(kt + (ew * 16 + fr) * 128 + sx * 32 + fq * 8);
; #pragma unroll
;             for (int i = 0; i < 8; ++i) { const int mm = sx * 32 + fq * 8 + i; const float x = bf2f((bfraw)raw[i]);
;               Af[sx][i] = (short)f2bf(x * __expf(lgf * (float)(127 - mm))); Ab[sx][i] = (short)f2bf(x * __expf(lgb * (float)mm)); } }
;           WAIT_V0(); __syncthreads();
;           f32x4 accf[8] = {}, accb[8] = {};
; #pragma unroll
;           for (int g2 = 0; g2 < 4; ++g2) { bf16x8 B[2][4];
; #pragma unroll
;             for (int q4 = 0; q4 < 2; ++q4)
; #pragma unroll
;               for (int sx = 0; sx < 4; ++sx) B[q4][sx] = RLD16(0, (g2 * 2 + q4) * 16 + fr, sx * 4 + fq);
;             SBAR();
; #pragma unroll
;             for (int q4 = 0; q4 < 2; ++q4)
; #pragma unroll
;               for (int sx = 0; sx < 4; ++sx) { accf[g2 * 2 + q4] = __builtin_amdgcn_mfma_f32_16x16x32_bf16(Af[sx], B[q4][sx], accf[g2 * 2 + q4], 0, 0, 0);
;                 accb[g2 * 2 + q4] = __builtin_amdgcn_mfma_f32_16x16x32_bf16(Ab[sx], B[q4][sx], accb[g2 * 2 + q4], 0, 0, 0); }
	s_waitcnt vmcnt(0)
	v_and_b32_e32 v65, 0xffff0000, v164
	v_lshlrev_b32_e32 v64, 16, v164
	v_or_b32_e32 v0, 0x62, v4
	v_cvt_f32_ubyte0_e32 v0, v0
	v_mul_f32_e32 v0, v10, v0
	v_mul_f32_e32 v0, 0x3fb8aa3b, v0
	v_pk_mul_f32 v[62:63], v[62:63], v[64:65]
	v_pk_mul_f32 v[6:7], v[6:7], v[64:65]
	v_exp_f32_e32 v64, v61
	v_exp_f32_e32 v66, v0
	v_or_b32_e32 v0, 0x63, v4
	v_xor_b32_e32 v61, 28, v4
	v_cvt_f32_ubyte0_e32 v61, v61
	v_cvt_f32_ubyte0_e32 v0, v0
	v_mul_f32_e32 v61, v11, v61
	v_mul_f32_e32 v0, v10, v0
	v_mul_f32_e32 v61, 0x3fb8aa3b, v61
	v_mul_f32_e32 v0, 0x3fb8aa3b, v0
	v_exp_f32_e32 v65, v61
	v_exp_f32_e32 v67, v0
	v_or_b32_e32 v61, 0x64, v4
	v_cvt_f32_ubyte0_e32 v61, v61
	v_mul_f32_e32 v61, v10, v61
	v_and_b32_e32 v69, 0xffff0000, v165
	v_lshlrev_b32_e32 v68, 16, v165
	v_mul_f32_e32 v61, 0x3fb8aa3b, v61
	v_pk_mul_f32 v[0:1], v[66:67], v[68:69]
	v_pk_mul_f32 v[64:65], v[64:65], v[68:69]
	v_xor_b32_e32 v66, 27, v4
	v_exp_f32_e32 v68, v61
	v_or_b32_e32 v61, 0x65, v4
	v_xor_b32_e32 v67, 26, v4
	v_cvt_f32_ubyte0_e32 v66, v66
	v_cvt_f32_ubyte0_e32 v67, v67
	v_cvt_f32_ubyte0_e32 v61, v61
	v_mul_f32_e32 v66, v11, v66
	v_mul_f32_e32 v67, v11, v67
	v_mul_f32_e32 v61, v10, v61
	v_mul_f32_e32 v66, 0x3fb8aa3b, v66
	v_mul_f32_e32 v67, 0x3fb8aa3b, v67
	v_mul_f32_e32 v61, 0x3fb8aa3b, v61
	v_exp_f32_e32 v66, v66
	v_exp_f32_e32 v67, v67
	v_exp_f32_e32 v69, v61
	v_and_b32_e32 v71, 0xffff0000, v166
	v_lshlrev_b32_e32 v70, 16, v166
	v_or_b32_e32 v2, 0x66, v4
	v_xor_b32_e32 v61, 25, v4
	v_cvt_f32_ubyte0_e32 v61, v61
	v_cvt_f32_ubyte0_e32 v2, v2
	v_mul_f32_e32 v61, v11, v61
	v_mul_f32_e32 v2, v10, v2
	v_mul_f32_e32 v61, 0x3fb8aa3b, v61
	v_mul_f32_e32 v2, 0x3fb8aa3b, v2
	v_pk_mul_f32 v[68:69], v[68:69], v[70:71]
	v_pk_mul_f32 v[66:67], v[66:67], v[70:71]
	v_exp_f32_e32 v70, v61
	v_exp_f32_e32 v72, v2
	v_or_b32_e32 v2, 0x67, v4
	v_xor_b32_e32 v61, 24, v4
	v_cvt_f32_ubyte0_e32 v61, v61
	v_cvt_f32_ubyte0_e32 v2, v2
	v_mul_f32_e32 v11, v11, v61
	v_mul_f32_e32 v2, v10, v2
	v_mul_f32_e32 v11, 0x3fb8aa3b, v11
	v_mul_f32_e32 v2, 0x3fb8aa3b, v2
	v_exp_f32_e32 v71, v11
	v_exp_f32_e32 v73, v2
	v_and_b32_e32 v11, 0xffff0000, v167
	v_lshlrev_b32_e32 v10, 16, v167
	v_pk_mul_f32 v[2:3], v[72:73], v[10:11]
	v_pk_mul_f32 v[10:11], v[70:71], v[10:11]
	v_cvt_pk_bf16_f32 v98, v10, v10
	v_cvt_pk_bf16_f32 v97, v67, v67
	v_cvt_pk_bf16_f32 v106, v3, v3
	v_bitop3_b32 v10, v5, v12, 4 bitop3:0x36
	v_cvt_pk_bf16_f32 v101, v0, v0
	v_bitop3_b32 v0, v9, v12, 3 bitop3:0x6c
	v_lshl_or_b32 v107, v10, 4, v176
	v_bitop3_b32 v10, v5, v12, 8 bitop3:0x36
	v_bitop3_b32 v5, v5, v12, 12 bitop3:0x36
	v_cvt_pk_bf16_f32 v94, v64, v64
	v_cvt_pk_bf16_f32 v95, v65, v65
	v_cvt_pk_bf16_f32 v96, v66, v66
	v_cvt_pk_bf16_f32 v61, v11, v11
	v_lshl_or_b32 v9, v0, 4, v176
	v_lshl_or_b32 v108, v10, 4, v176
	v_lshl_or_b32 v5, v5, 4, v176
	v_cvt_pk_bf16_f32 v6, v6, v6
	v_cvt_pk_bf16_f32 v7, v7, v7
	v_cvt_pk_bf16_f32 v99, v62, v62
	v_cvt_pk_bf16_f32 v100, v63, v63
	v_cvt_pk_bf16_f32 v102, v1, v1
	v_cvt_pk_bf16_f32 v103, v68, v68
	v_cvt_pk_bf16_f32 v104, v69, v69
	v_cvt_pk_bf16_f32 v105, v2, v2
	ds_read_b128 v[0:3], v9
	ds_read_b128 v[62:65], v107
	ds_read_b128 v[66:69], v108
	ds_read_b128 v[70:73], v5
	ds_read_b128 v[74:77], v9 offset:4096
	ds_read_b128 v[78:81], v107 offset:4096
	ds_read_b128 v[82:85], v108 offset:4096
	ds_read_b128 v[86:89], v5 offset:4096
	v_perm_b32 v93, v23, v21, s58
	v_perm_b32 v92, v19, v17, s58
	v_perm_b32 v91, v16, v15, s58
	v_perm_b32 v90, v14, v13, s58
	v_perm_b32 v13, v28, v27, s58
	v_perm_b32 v12, v26, v25, s58
	v_perm_b32 v11, v24, v22, s58
	v_perm_b32 v10, v20, v18, s58
	v_perm_b32 v21, v38, v37, s58
	v_perm_b32 v20, v34, v33, s58
	v_perm_b32 v19, v32, v31, s58
	v_perm_b32 v18, v30, v29, s58
	v_perm_b32 v25, v44, v43, s58
	v_perm_b32 v24, v42, v41, s58
	v_perm_b32 v23, v40, v39, s58
	v_perm_b32 v22, v36, v35, s58
	s_waitcnt lgkmcnt(7)
	v_mfma_f32_16x16x32_bf16 v[14:17], v[90:93], v[0:3], 0
	v_perm_b32 v28, v50, v49, s58
	v_perm_b32 v27, v48, v47, s58
	v_perm_b32 v26, v46, v45, s58
	v_mfma_f32_16x16x32_bf16 v[0:3], v[10:13], v[0:3], 0
	v_perm_b32 v29, v54, v53, s58
	v_perm_b32 v33, v60, v59, s58
	v_perm_b32 v32, v58, v57, s58
	s_waitcnt lgkmcnt(3)
	v_mfma_f32_16x16x32_bf16 v[42:45], v[90:93], v[74:77], 0
	v_perm_b32 v31, v56, v55, s58
	v_perm_b32 v30, v52, v51, s58
	v_perm_b32 v37, v61, v98, s58
	v_mfma_f32_16x16x32_bf16 v[46:49], v[10:13], v[74:77], 0
	v_perm_b32 v36, v97, v96, s58
	v_perm_b32 v35, v95, v94, s58
	v_perm_b32 v34, v7, v6, s58
	v_mfma_f32_16x16x32_bf16 v[14:17], v[18:21], v[62:65], v[14:17]
	v_perm_b32 v41, v106, v105, s58
	v_perm_b32 v40, v104, v103, s58
	v_perm_b32 v39, v102, v101, s58
	v_mfma_f32_16x16x32_bf16 v[0:3], v[22:25], v[62:65], v[0:3]
	v_perm_b32 v38, v100, v99, s58
	s_waitcnt lgkmcnt(2)
	v_mfma_f32_16x16x32_bf16 v[42:45], v[18:21], v[78:81], v[42:45]
	v_mfma_f32_16x16x32_bf16 v[46:49], v[22:25], v[78:81], v[46:49]
	v_mfma_f32_16x16x32_bf16 v[14:17], v[26:29], v[66:69], v[14:17]
	v_mfma_f32_16x16x32_bf16 v[0:3], v[30:33], v[66:69], v[0:3]
	s_waitcnt lgkmcnt(1)
	v_mfma_f32_16x16x32_bf16 v[42:45], v[26:29], v[82:85], v[42:45]
	v_mfma_f32_16x16x32_bf16 v[46:49], v[30:33], v[82:85], v[46:49]
	v_mfma_f32_16x16x32_bf16 v[14:17], v[34:37], v[70:73], v[14:17]
	v_mfma_f32_16x16x32_bf16 v[0:3], v[38:41], v[70:73], v[0:3]
	s_waitcnt lgkmcnt(0)
	v_mfma_f32_16x16x32_bf16 v[42:45], v[34:37], v[86:89], v[42:45]
	v_mfma_f32_16x16x32_bf16 v[46:49], v[38:41], v[86:89], v[46:49]
	ds_read_b128 v[50:53], v9 offset:8192
	ds_read_b128 v[54:57], v9 offset:12288
	ds_read_b128 v[58:61], v107 offset:8192
	ds_read_b128 v[62:65], v107 offset:12288
	ds_read_b128 v[66:69], v108 offset:8192
	ds_read_b128 v[70:73], v108 offset:12288
	ds_read_b128 v[74:77], v5 offset:8192
	ds_read_b128 v[78:81], v5 offset:12288
	s_waitcnt lgkmcnt(7)
; #define SBAR() __builtin_amdgcn_sched_barrier(0)
; __global__ void __launch_bounds__(512) mega(Params p) {
;     ...
;           for (int g2 = 0; g2 < 4; ++g2) { bf16x8 B[2][4];
; #pragma unroll
;             for (int q4 = 0; q4 < 2; ++q4)
; #pragma unroll
;               for (int sx = 0; sx < 4; ++sx) B[q4][sx] = RLD16(0, (g2 * 2 + q4) * 16 + fr, sx * 4 + fq);
;             SBAR();
; #pragma unroll
;             for (int q4 = 0; q4 < 2; ++q4)
; #pragma unroll
;               for (int sx = 0; sx < 4; ++sx) { accf[g2 * 2 + q4] = __builtin_amdgcn_mfma_f32_16x16x32_bf16(Af[sx], B[q4][sx], accf[g2 * 2 + q4], 0, 0, 0);
;                 accb[g2 * 2 + q4] = __builtin_amdgcn_mfma_f32_16x16x32_bf16(Ab[sx], B[q4][sx], accb[g2 * 2 + q4], 0, 0, 0); }
;             SBAR(); }
	v_mfma_f32_16x16x32_bf16 v[82:85], v[90:93], v[50:53], 0
	v_mfma_f32_16x16x32_bf16 v[50:53], v[10:13], v[50:53], 0
	s_waitcnt lgkmcnt(5)
	v_mfma_f32_16x16x32_bf16 v[82:85], v[18:21], v[58:61], v[82:85]
	v_mfma_f32_16x16x32_bf16 v[50:53], v[22:25], v[58:61], v[50:53]
	s_waitcnt lgkmcnt(3)
	v_mfma_f32_16x16x32_bf16 v[58:61], v[26:29], v[66:69], v[82:85]
	v_mfma_f32_16x16x32_bf16 v[50:53], v[30:33], v[66:69], v[50:53]
	v_mfma_f32_16x16x32_bf16 v[66:69], v[90:93], v[54:57], 0
	v_mfma_f32_16x16x32_bf16 v[54:57], v[10:13], v[54:57], 0
	v_mfma_f32_16x16x32_bf16 v[66:69], v[18:21], v[62:65], v[66:69]
	v_mfma_f32_16x16x32_bf16 v[54:57], v[22:25], v[62:65], v[54:57]
	s_waitcnt lgkmcnt(2)
	v_mfma_f32_16x16x32_bf16 v[62:65], v[26:29], v[70:73], v[66:69]
	v_mfma_f32_16x16x32_bf16 v[54:57], v[30:33], v[70:73], v[54:57]
	s_waitcnt lgkmcnt(1)
	v_mfma_f32_16x16x32_bf16 v[58:61], v[34:37], v[74:77], v[58:61]
	v_mfma_f32_16x16x32_bf16 v[50:53], v[38:41], v[74:77], v[50:53]
	s_waitcnt lgkmcnt(0)
	v_mfma_f32_16x16x32_bf16 v[62:65], v[34:37], v[78:81], v[62:65]
	v_mfma_f32_16x16x32_bf16 v[54:57], v[38:41], v[78:81], v[54:57]
	ds_read_b128 v[66:69], v9 offset:16384
	ds_read_b128 v[70:73], v9 offset:20480
	ds_read_b128 v[74:77], v107 offset:16384
	ds_read_b128 v[78:81], v107 offset:20480
	ds_read_b128 v[82:85], v108 offset:16384
	ds_read_b128 v[86:89], v108 offset:20480
	ds_read_b128 v[94:97], v5 offset:16384
	ds_read_b128 v[98:101], v5 offset:20480
	s_waitcnt lgkmcnt(7)
	v_mfma_f32_16x16x32_bf16 v[102:105], v[90:93], v[66:69], 0
	v_mfma_f32_16x16x32_bf16 v[66:69], v[10:13], v[66:69], 0
	s_waitcnt lgkmcnt(5)
	v_mfma_f32_16x16x32_bf16 v[102:105], v[18:21], v[74:77], v[102:105]
	v_mfma_f32_16x16x32_bf16 v[66:69], v[22:25], v[74:77], v[66:69]
	s_waitcnt lgkmcnt(3)
	v_mfma_f32_16x16x32_bf16 v[74:77], v[26:29], v[82:85], v[102:105]
	v_mfma_f32_16x16x32_bf16 v[66:69], v[30:33], v[82:85], v[66:69]
	v_mfma_f32_16x16x32_bf16 v[82:85], v[90:93], v[70:73], 0
	v_mfma_f32_16x16x32_bf16 v[70:73], v[10:13], v[70:73], 0
	v_mfma_f32_16x16x32_bf16 v[82:85], v[18:21], v[78:81], v[82:85]
	v_mfma_f32_16x16x32_bf16 v[70:73], v[22:25], v[78:81], v[70:73]
	s_waitcnt lgkmcnt(2)
	v_mfma_f32_16x16x32_bf16 v[78:81], v[26:29], v[86:89], v[82:85]
	v_mfma_f32_16x16x32_bf16 v[70:73], v[30:33], v[86:89], v[70:73]
	s_waitcnt lgkmcnt(1)
	v_mfma_f32_16x16x32_bf16 v[74:77], v[34:37], v[94:97], v[74:77]
	v_mfma_f32_16x16x32_bf16 v[66:69], v[38:41], v[94:97], v[66:69]
	s_waitcnt lgkmcnt(0)
	v_mfma_f32_16x16x32_bf16 v[78:81], v[34:37], v[98:101], v[78:81]
	v_mfma_f32_16x16x32_bf16 v[70:73], v[38:41], v[98:101], v[70:73]
	ds_read_b128 v[82:85], v9 offset:24576
	ds_read_b128 v[86:89], v9 offset:28672
	ds_read_b128 v[94:97], v107 offset:24576
	ds_read_b128 v[98:101], v107 offset:28672
	ds_read_b128 v[102:105], v108 offset:24576
	ds_read_b128 v[106:109], v108 offset:28672
	ds_read_b128 v[110:113], v5 offset:24576
	ds_read_b128 v[114:117], v5 offset:28672
	s_waitcnt lgkmcnt(7)
	v_mfma_f32_16x16x32_bf16 v[118:121], v[90:93], v[82:85], 0
	v_mfma_f32_16x16x32_bf16 v[82:85], v[10:13], v[82:85], 0
	s_waitcnt lgkmcnt(6)
	v_mfma_f32_16x16x32_bf16 v[90:93], v[90:93], v[86:89], 0
	v_mfma_f32_16x16x32_bf16 v[10:13], v[10:13], v[86:89], 0
	s_waitcnt lgkmcnt(5)
	v_mfma_f32_16x16x32_bf16 v[118:121], v[18:21], v[94:97], v[118:121]
	v_mfma_f32_16x16x32_bf16 v[82:85], v[22:25], v[94:97], v[82:85]
	s_waitcnt lgkmcnt(4)
	v_mfma_f32_16x16x32_bf16 v[18:21], v[18:21], v[98:101], v[90:93]
	v_mfma_f32_16x16x32_bf16 v[10:13], v[22:25], v[98:101], v[10:13]
	s_waitcnt lgkmcnt(3)
	v_mfma_f32_16x16x32_bf16 v[94:97], v[26:29], v[102:105], v[118:121]
	v_mfma_f32_16x16x32_bf16 v[82:85], v[30:33], v[102:105], v[82:85]
	s_waitcnt lgkmcnt(2)
; #define SBAR() __builtin_amdgcn_sched_barrier(0)
; __global__ void __launch_bounds__(512) mega(Params p) {
;     ...
;         for (int bi = bid; bi < 128 * 8; bi += nb) {
;     ...
;               for (int sx = 0; sx < 4; ++sx) { accf[g2 * 2 + q4] = __builtin_amdgcn_mfma_f32_16x16x32_bf16(Af[sx], B[q4][sx], accf[g2 * 2 + q4], 0, 0, 0);
;                 accb[g2 * 2 + q4] = __builtin_amdgcn_mfma_f32_16x16x32_bf16(Ab[sx], B[q4][sx], accb[g2 * 2 + q4], 0, 0, 0); }
;             SBAR(); }
;           bfraw* of = kv_ + ((long)((chunk * 8 + head) * 2 + 0)) * 16384 + fr * 128 + ew * 16 + fq * 4; bfraw* ob = of + 16384;
; #pragma unroll
;           for (int n = 0; n < 8; ++n) { u32x2 pf_ = {cvtpk(accf[n][0], accf[n][1]), cvtpk(accf[n][2], accf[n][3])}; u32x2 pb_ = {cvtpk(accb[n][0], accb[n][1]), cvtpk(accb[n][2], accb[n][3])};
;             *(u32x2*)(of + n * 2048) = pf_; *(u32x2*)(ob + n * 2048) = pb_; }
;         }
	v_mfma_f32_16x16x32_bf16 v[18:21], v[26:29], v[106:109], v[18:21]
	v_mfma_f32_16x16x32_bf16 v[10:13], v[30:33], v[106:109], v[10:13]
	s_waitcnt lgkmcnt(1)
	v_mfma_f32_16x16x32_bf16 v[94:97], v[34:37], v[110:113], v[94:97]
	v_mfma_f32_16x16x32_bf16 v[82:85], v[38:41], v[110:113], v[82:85]
	s_waitcnt lgkmcnt(0)
	v_mfma_f32_16x16x32_bf16 v[18:21], v[34:37], v[114:117], v[18:21]
	v_mfma_f32_16x16x32_bf16 v[10:13], v[38:41], v[114:117], v[10:13]
	s_ashr_i32 s17, s16, 31
	s_lshl_b64 s[20:21], s[16:17], 15
	s_add_u32 s20, s2, s20
	s_addc_u32 s21, s3, s21
	s_lshl_b32 s18, s18, 4
	v_lshl_add_u64 v[6:7], s[20:21], 0, v[176:177]
	s_ashr_i32 s19, s18, 31
	v_lshl_add_u64 v[6:7], s[18:19], 1, v[6:7]
	v_mov_b32_e32 v5, v177
	v_lshl_add_u64 v[4:5], v[6:7], 0, v[4:5]
	s_mov_b32 s17, 0x9000
	v_cvt_pk_bf16_f32 v6, v14, v15
	v_cvt_pk_bf16_f32 v7, v16, v17
	v_cvt_pk_bf16_f32 v0, v0, v1
	v_cvt_pk_bf16_f32 v1, v2, v3
	v_add_co_u32_e32 v2, vcc, s17, v4
	global_store_dwordx2 v[4:5], v[6:7], off
	s_nop 0
	v_addc_co_u32_e32 v3, vcc, 0, v5, vcc
	v_add_co_u32_e32 v14, vcc, s53, v4
	global_store_dwordx2 v[2:3], v[0:1], off offset:-4096
	v_cvt_pk_bf16_f32 v0, v42, v43
	v_cvt_pk_bf16_f32 v1, v44, v45
	s_nop 0
	v_addc_co_u32_e32 v15, vcc, 0, v5, vcc
	v_cvt_pk_bf16_f32 v6, v46, v47
	v_cvt_pk_bf16_f32 v7, v48, v49
	global_store_dwordx2 v[14:15], v[0:1], off offset:-4096
	global_store_dwordx2 v[2:3], v[6:7], off
	v_cvt_pk_bf16_f32 v0, v58, v59
	s_mov_b32 s17, 0xb000
	v_cvt_pk_bf16_f32 v1, v60, v61
	v_cvt_pk_bf16_f32 v2, v50, v51
	v_cvt_pk_bf16_f32 v3, v52, v53
	global_store_dwordx2 v[14:15], v[0:1], off
	v_add_co_u32_e32 v0, vcc, s17, v4
	s_mov_b32 s17, 0xd000
	s_nop 0
	v_addc_co_u32_e32 v1, vcc, 0, v5, vcc
	v_add_co_u32_e32 v14, vcc, s83, v4
	global_store_dwordx2 v[0:1], v[2:3], off offset:-4096
	v_cvt_pk_bf16_f32 v2, v62, v63
	v_cvt_pk_bf16_f32 v3, v64, v65
	s_nop 0
	v_addc_co_u32_e32 v15, vcc, 0, v5, vcc
	v_cvt_pk_bf16_f32 v6, v54, v55
	v_cvt_pk_bf16_f32 v7, v56, v57
	global_store_dwordx2 v[14:15], v[2:3], off offset:-4096
	global_store_dwordx2 v[0:1], v[6:7], off
	v_cvt_pk_bf16_f32 v0, v74, v75
	v_cvt_pk_bf16_f32 v1, v76, v77
	v_cvt_pk_bf16_f32 v2, v66, v67
	v_cvt_pk_bf16_f32 v3, v68, v69
	global_store_dwordx2 v[14:15], v[0:1], off
	v_add_co_u32_e32 v0, vcc, s17, v4
	s_movk_i32 s17, 0x6000
	s_nop 0
	v_addc_co_u32_e32 v1, vcc, 0, v5, vcc
	v_add_co_u32_e32 v14, vcc, s17, v4
	global_store_dwordx2 v[0:1], v[2:3], off offset:-4096
	v_cvt_pk_bf16_f32 v2, v78, v79
	v_cvt_pk_bf16_f32 v3, v80, v81
	s_nop 0
	v_addc_co_u32_e32 v15, vcc, 0, v5, vcc
	s_add_i32 s15, s15, s28
	v_cvt_pk_bf16_f32 v6, v70, v71
	v_cvt_pk_bf16_f32 v7, v72, v73
	global_store_dwordx2 v[14:15], v[2:3], off offset:-4096
	global_store_dwordx2 v[0:1], v[6:7], off
	v_cvt_pk_bf16_f32 v0, v94, v95
	s_mov_b32 s17, 0xf000
	s_add_u32 s12, s12, s72
	v_cvt_pk_bf16_f32 v1, v96, v97
	v_cvt_pk_bf16_f32 v2, v82, v83
	v_cvt_pk_bf16_f32 v3, v84, v85
	global_store_dwordx2 v[14:15], v[0:1], off
	v_add_co_u32_e32 v0, vcc, s17, v4
	s_addc_u32 s14, s14, s73
	s_nop 0
	v_addc_co_u32_e32 v1, vcc, 0, v5, vcc
	s_movk_i32 s17, 0x7000
	s_add_u32 s8, s8, s72
	v_add_co_u32_e32 v4, vcc, s17, v4
	s_addc_u32 s9, s9, s73
	s_add_i32 s16, s16, s59
	v_addc_co_u32_e32 v5, vcc, 0, v5, vcc
	s_cmpk_gt_i32 s15, 0x3ff
	global_store_dwordx2 v[0:1], v[2:3], off offset:-4096
	v_cvt_pk_bf16_f32 v2, v18, v19
	v_cvt_pk_bf16_f32 v3, v20, v21
	v_cvt_pk_bf16_f32 v6, v10, v11
	v_cvt_pk_bf16_f32 v7, v12, v13
	global_store_dwordx2 v[4:5], v[2:3], off
	global_store_dwordx2 v[0:1], v[6:7], off
	s_cbranch_scc0 .LBB0_2423
